# LRU gate-weight staging: 16 serialized flat loads hoisted into one batch
# speedup vs baseline: 1.0126x; 1.0029x over previous
.LBB0_1058:
	v_mov_b32_e32 v0, s22
	v_add_co_u32_e32 v8, vcc, 0x80000, v0
	v_mov_b32_e32 v0, s23
	v_mov_b32_e32 v56, v214
	v_addc_co_u32_e32 v9, vcc, 0, v0, vcc
	flat_load_dwordx4 v[0:3], v[8:9] offset:152
	flat_load_dwordx4 v[46:49], v[8:9] offset:136
	flat_load_dwordx4 v[4:7], v[8:9] offset:168
	flat_load_dwordx2 v[16:17], v[8:9] offset:184
	v_readlane_b32 s2, v254, 51
	s_lshl_b32 s0, s27, 12
	v_readlane_b32 s3, v254, 52
	s_mov_b32 s1, s3
	s_or_b32 s0, s2, s0
	s_lshl_b64 s[0:1], s[0:1], 2
	v_ashrrev_i32_e32 v57, 31, v56
	v_lshlrev_b64 v[10:11], 2, v[56:57]
	v_and_b32_e32 v88, 63, v56
	s_movk_i32 s16, 0x2000
	v_readfirstlane_b32 s2, v56
	s_waitcnt vmcnt(0) lgkmcnt(0)
	v_lshl_add_u64 v[0:1], v[0:1], 0, s[0:1]
	v_lshl_add_u64 v[12:13], v[0:1], 0, v[10:11]
	v_lshl_add_u64 v[4:5], v[4:5], 0, s[0:1]
	v_lshl_add_u64 v[4:5], v[4:5], 0, v[10:11]
	global_load_dword v18, v[12:13], off
	global_load_dword v19, v[12:13], off offset:2048
	global_load_dword v26, v[4:5], off
	global_load_dword v27, v[4:5], off offset:2048
	v_add_co_u32_e32 v34, vcc, 0x1000, v12
	s_nop 1
	v_addc_co_u32_e32 v35, vcc, 0, v13, vcc
	v_add_co_u32_e32 v36, vcc, 0x1000, v4
	s_nop 1
	v_addc_co_u32_e32 v37, vcc, 0, v5, vcc
	global_load_dword v20, v[34:35], off
	global_load_dword v21, v[34:35], off offset:2048
	global_load_dword v28, v[36:37], off
	global_load_dword v29, v[36:37], off offset:2048
	v_add_co_u32_e32 v34, vcc, 0x2000, v12
	s_nop 1
	v_addc_co_u32_e32 v35, vcc, 0, v13, vcc
	v_add_co_u32_e32 v36, vcc, 0x2000, v4
	s_nop 1
	v_addc_co_u32_e32 v37, vcc, 0, v5, vcc
	global_load_dword v22, v[34:35], off
	global_load_dword v23, v[34:35], off offset:2048
	global_load_dword v30, v[36:37], off
	global_load_dword v31, v[36:37], off offset:2048
	v_add_co_u32_e32 v34, vcc, 0x3000, v12
	s_nop 1
	v_addc_co_u32_e32 v35, vcc, 0, v13, vcc
	v_add_co_u32_e32 v36, vcc, 0x3000, v4
	s_nop 1
	v_addc_co_u32_e32 v37, vcc, 0, v5, vcc
	global_load_dword v24, v[34:35], off
	global_load_dword v25, v[34:35], off offset:2048
	global_load_dword v32, v[36:37], off
	global_load_dword v33, v[36:37], off offset:2048
	v_ashrrev_i32_e32 v10, 5, v56
	s_movk_i32 s0, 0x90
	v_mad_u32_u24 v14, v88, s0, 0
	v_and_b32_e32 v10, -2, v10
	v_add_u32_e32 v10, v14, v10
	v_mov_b32_e32 v0, v16
	v_mov_b32_e32 v1, v17
	s_waitcnt vmcnt(0)
	v_cvt_pk_bf16_f32 v38, v18, v113
	ds_write_b16 v10, v38
	v_cvt_pk_bf16_f32 v39, v26, v113
	ds_write_b16 v10, v39 offset:9216
	v_cvt_pk_bf16_f32 v40, v19, v113
	ds_write_b16 v10, v40 offset:16
	v_cvt_pk_bf16_f32 v41, v27, v113
	ds_write_b16 v10, v41 offset:9232
	v_cvt_pk_bf16_f32 v42, v20, v113
	ds_write_b16 v10, v42 offset:32
	v_cvt_pk_bf16_f32 v43, v28, v113
	ds_write_b16 v10, v43 offset:9248
	v_cvt_pk_bf16_f32 v44, v21, v113
	ds_write_b16 v10, v44 offset:48
	v_cvt_pk_bf16_f32 v45, v29, v113
	ds_write_b16 v10, v45 offset:9264
	v_cvt_pk_bf16_f32 v38, v22, v113
	ds_write_b16 v10, v38 offset:64
	v_cvt_pk_bf16_f32 v39, v30, v113
	ds_write_b16 v10, v39 offset:9280
	v_cvt_pk_bf16_f32 v40, v23, v113
	ds_write_b16 v10, v40 offset:80
	v_cvt_pk_bf16_f32 v41, v31, v113
	ds_write_b16 v10, v41 offset:9296
	v_cvt_pk_bf16_f32 v42, v24, v113
	ds_write_b16 v10, v42 offset:96
	v_cvt_pk_bf16_f32 v43, v32, v113
	ds_write_b16 v10, v43 offset:9312
	v_cvt_pk_bf16_f32 v44, v25, v113
	ds_write_b16 v10, v44 offset:112
	v_cvt_pk_bf16_f32 v45, v33, v113
	ds_write_b16 v10, v45 offset:9328
	s_movk_i32 s0, 0x80
	v_cmp_gt_i32_e32 vcc, s0, v56
	s_and_saveexec_b64 s[0:1], vcc
	v_lshl_add_u32 v4, v56, 2, 0
	v_add_u32_e32 v4, 0x1b000, v4
	ds_write_b32 v4, v113
	s_or_b64 exec, exec, s[0:1]
	v_readlane_b32 s0, v254, 49
	v_readlane_b32 s1, v254, 50
	s_lshl_b64 s[0:1], s[0:1], 2
	s_nop 0
	v_lshl_add_u64 v[4:5], v[6:7], 0, s[0:1]
	v_lshl_add_u64 v[6:7], v[0:1], 0, s[0:1]
	v_lshrrev_b32_e32 v0, 2, v56
	v_lshl_add_u64 v[2:3], v[2:3], 0, s[0:1]
	v_and_b32_e32 v57, 12, v0
	v_readlane_b32 s0, v254, 53
	s_nop 1
	v_or_b32_e32 v0, s0, v57
	v_lshlrev_b32_e32 v112, 2, v0
	v_lshl_add_u64 v[32:33], v[6:7], 0, v[112:113]
	v_lshl_add_u64 v[28:29], v[2:3], 0, v[112:113]
	flat_load_dwordx4 v[8:11], v[32:33]
	v_lshl_add_u64 v[30:31], v[4:5], 0, v[112:113]
	flat_load_dwordx4 v[0:3], v[28:29]
	flat_load_dwordx4 v[4:7], v[30:31]
	s_mov_b32 s0, 0xc1a00000
	s_waitcnt vmcnt(0) lgkmcnt(0)
	v_xor_b32_e32 v50, 0x80000000, v8
	v_cmp_ngt_f32_e32 vcc, s0, v8
	s_and_saveexec_b64 s[0:1], vcc
	v_readlane_b32 s17, v254, 54
	s_cbranch_execz .LBB0_1062
	v_mul_f32_e32 v8, 0xbfb8aa3b, v8
	v_exp_f32_e32 v8, v8
	s_mov_b32 s3, 0x3f2aaaab
	v_add_f32_e32 v14, 1.0, v8
	v_frexp_mant_f32_e32 v16, v14
	v_cvt_f64_f32_e32 v[12:13], v14
	v_frexp_exp_i32_f64_e32 v12, v[12:13]
	v_cmp_gt_f32_e32 vcc, s3, v16
	v_add_f32_e32 v15, -1.0, v14
	v_sub_f32_e32 v17, v15, v14
	v_subbrev_co_u32_e32 v20, vcc, 0, v12, vcc
	v_sub_u32_e32 v12, 0, v20
	v_sub_f32_e32 v15, v8, v15
	v_add_f32_e32 v17, 1.0, v17
	v_ldexp_f32 v13, v14, v12
	v_add_f32_e32 v15, v15, v17
	v_add_f32_e32 v14, -1.0, v13
	v_add_f32_e32 v16, 1.0, v13
	v_ldexp_f32 v12, v15, v12
	v_add_f32_e32 v15, 1.0, v14
	v_add_f32_e32 v17, -1.0, v16
	v_sub_f32_e32 v15, v13, v15
	v_sub_f32_e32 v13, v13, v17
	v_add_f32_e32 v15, v12, v15
	v_add_f32_e32 v12, v12, v13
	v_add_f32_e32 v21, v16, v12
	v_rcp_f32_e32 v23, v21
	v_sub_f32_e32 v13, v21, v16
	v_sub_f32_e32 v22, v12, v13
	v_add_f32_e32 v13, v14, v15
	v_mul_f32_e32 v25, v13, v23
	v_sub_f32_e32 v12, v13, v14
	v_mul_f32_e32 v14, v21, v25
	v_fma_f32 v16, v25, v21, -v14
	v_fmac_f32_e32 v16, v25, v22
	v_sub_f32_e32 v24, v15, v12
	v_add_f32_e32 v12, v14, v16
	v_sub_f32_e32 v15, v13, v12
	v_pk_add_f32 v[18:19], v[12:13], v[14:15] neg_lo:[0,1] neg_hi:[0,1]
	v_mov_b32_e32 v17, v12
	v_pk_add_f32 v[12:13], v[18:19], v[16:17] neg_lo:[0,1] neg_hi:[0,1]
	s_mov_b32 s3, 0x3f317218
	v_add_f32_e32 v13, v24, v13
	v_add_f32_e32 v12, v12, v13
	v_add_f32_e32 v13, v15, v12
	v_mul_f32_e32 v24, v23, v13
	v_mul_f32_e32 v14, v21, v24
	v_fma_f32 v16, v24, v21, -v14
	v_fmac_f32_e32 v16, v24, v22
	v_sub_f32_e32 v15, v15, v13
	v_add_f32_e32 v21, v12, v15
	v_add_f32_e32 v12, v14, v16
	v_sub_f32_e32 v15, v13, v12
	v_pk_add_f32 v[18:19], v[12:13], v[14:15] neg_lo:[0,1] neg_hi:[0,1]
	v_mov_b32_e32 v17, v12
	v_pk_add_f32 v[12:13], v[18:19], v[16:17] neg_lo:[0,1] neg_hi:[0,1]
	s_nop 0
	v_add_f32_e32 v13, v21, v13
	v_add_f32_e32 v12, v12, v13
	v_add_f32_e32 v13, v25, v24
	v_add_f32_e32 v12, v15, v12
	v_sub_f32_e32 v14, v13, v25
	v_mul_f32_e32 v12, v23, v12
	v_sub_f32_e32 v14, v24, v14
	v_add_f32_e32 v14, v14, v12
	v_add_f32_e32 v16, v13, v14
	v_mul_f32_e32 v17, v16, v16
	v_fmamk_f32 v12, v17, 0x3e9b6dac, v216
	v_fmaak_f32 v195, v17, v12, 0x3f2aaada
	v_cvt_f32_i32_e32 v12, v20
	v_sub_f32_e32 v13, v16, v13
	v_sub_f32_e32 v13, v14, v13
	v_ldexp_f32 v18, v13, 1
	v_mul_f32_e32 v13, v16, v17
	v_ldexp_f32 v15, v16, 1
	v_pk_mul_f32 v[16:17], v[12:13], v[194:195]
	s_nop 0
	v_fma_f32 v14, v12, s3, -v16
	v_fmac_f32_e32 v14, 0xb102e308, v12
	v_pk_add_f32 v[12:13], v[16:17], v[14:15]
	s_mov_b32 s3, 0x7f800000
	v_sub_f32_e32 v15, v13, v15
	v_sub_f32_e32 v15, v17, v15
	v_add_f32_e32 v19, v18, v15
	v_mov_b32_e32 v18, v16
	v_pk_add_f32 v[16:17], v[12:13], v[16:17] neg_lo:[0,1] neg_hi:[0,1]
	v_pk_add_f32 v[20:21], v[12:13], v[18:19]
	v_mov_b32_e32 v15, v12
	v_mov_b32_e32 v17, v21
	v_pk_add_f32 v[22:23], v[14:15], v[16:17] neg_lo:[0,1] neg_hi:[0,1]
	v_pk_add_f32 v[14:15], v[14:15], v[16:17]
	v_mov_b32_e32 v18, v19
	v_pk_add_f32 v[16:17], v[14:15], v[12:13] op_sel:[1,0] op_sel_hi:[0,1] neg_lo:[0,1] neg_hi:[0,1]
	v_pk_add_f32 v[24:25], v[20:21], v[16:17] op_sel_hi:[1,0] neg_lo:[0,1] neg_hi:[0,1]
	v_mov_b32_e32 v20, v21
	v_mov_b32_e32 v21, v15
	v_pk_mov_b32 v[16:17], v[12:13], v[16:17] op_sel:[1,0]
	v_mov_b32_e32 v19, v12
	v_pk_add_f32 v[16:17], v[20:21], v[16:17] neg_lo:[0,1] neg_hi:[0,1]
	v_mov_b32_e32 v24, v22
	v_pk_add_f32 v[12:13], v[18:19], v[16:17] neg_lo:[0,1] neg_hi:[0,1]
	v_mov_b32_e32 v23, v15
	v_pk_add_f32 v[16:17], v[24:25], v[12:13]
	v_cmp_neq_f32_e32 vcc, s3, v8
	v_pk_add_f32 v[18:19], v[16:17], v[16:17] op_sel:[0,1] op_sel_hi:[1,0]
	s_mov_b32 s3, 0x33800000
	v_pk_add_f32 v[14:15], v[14:15], v[18:19] op_sel:[1,0] op_sel_hi:[0,1]
	v_mov_b32_e32 v17, v14
	v_pk_add_f32 v[20:21], v[16:17], v[22:23] neg_lo:[0,1] neg_hi:[0,1]
	v_mov_b32_e32 v13, v18
	v_sub_f32_e32 v15, v16, v20
	v_pk_add_f32 v[12:13], v[12:13], v[20:21] neg_lo:[0,1] neg_hi:[0,1]
	v_sub_f32_e32 v15, v22, v15
	v_add_f32_e32 v12, v12, v15
	v_add_f32_e32 v12, v12, v13
	v_add_f32_e32 v12, v14, v12
	v_cndmask_b32_e32 v12, v221, v12, vcc
	v_cmp_ngt_f32_e32 vcc, -1.0, v8
	s_nop 1
	v_cndmask_b32_e32 v12, v224, v12, vcc
	v_cmp_neq_f32_e32 vcc, -1.0, v8
	s_nop 1
	v_cndmask_b32_e32 v12, v223, v12, vcc
	v_cmp_lt_f32_e64 vcc, |v8|, s3
	s_nop 1
	v_cndmask_b32_e32 v50, v12, v8, vcc
